# v10 + mixer B compressed branch: 64 per-element bias lookups batched (NEG word instead of exec masks), second pass loop rewritten with batched K-frag reads and lookups
# speedup vs baseline: 1.0113x; 1.0111x over previous
.LBB0_1252:
	s_or_b64 exec, exec, s[8:9]
	s_lshl_b32 s8, s7, 3
	s_or_b32 s8, s8, s56
	s_bfe_u32 s66, s8, 0x30001
	v_ashrrev_i32_e32 v86, 3, v87
	v_lshl_add_u32 v2, s66, 7, v86
	v_lshlrev_b32_e32 v0, 4, v84
	v_ashrrev_i32_e32 v3, 31, v2
	v_and_b32_e32 v131, 0x70, v0
	v_lshlrev_b64 v[10:11], 8, v[2:3]
	s_lshl_b32 s46, s6, 1
	v_or3_b32 v10, v131, s46, v10
	s_mov_b64 s[8:9], 0x4000
	v_lshl_add_u64 v[2:3], s[58:59], 0, v[10:11]
	v_lshl_add_u64 v[6:7], s[60:61], 0, v[10:11]
	v_lshl_add_u64 v[10:11], v[10:11], 0, s[8:9]
	v_lshl_add_u64 v[12:13], s[58:59], 0, v[10:11]
	v_lshl_add_u64 v[14:15], s[60:61], 0, v[10:11]
	global_load_dwordx4 v[2:5], v[2:3], off
	s_nop 0
	global_load_dwordx4 v[6:9], v[6:7], off
	s_nop 0
	global_load_dwordx4 v[10:13], v[12:13], off
	s_nop 0
	global_load_dwordx4 v[14:17], v[14:15], off
	s_lshl_b32 s7, s7, 4
	s_andn2_b32 s7, s7, 31
	s_sub_i32 s16, 0x7e0, s7
	v_and_b32_e32 v85, 31, v84
	v_or_b32_e32 v193, s16, v85
	v_ashrrev_i32_e32 v0, 5, v84
	v_lshl_add_u32 v132, s66, 11, v193
	v_mov_b64_e32 v[18:19], s[50:51]
	v_mad_i64_i32 v[82:83], s[8:9], v132, s84, v[18:19]
	s_lshl_b32 s72, s34, 1
	s_mov_b32 s73, s67
	v_lshlrev_b32_e32 v20, 3, v0
	v_lshl_add_u64 v[18:19], v[82:83], 0, s[72:73]
	v_ashrrev_i32_e32 v21, 31, v20
	v_lshl_add_u64 v[18:19], v[20:21], 1, v[18:19]
	global_load_dwordx4 v[98:101], v[18:19], off offset:2560
	global_load_dwordx4 v[102:105], v[18:19], off offset:2592
	global_load_dwordx4 v[106:109], v[18:19], off offset:2624
	global_load_dwordx4 v[110:113], v[18:19], off offset:2656
	v_lshrrev_b32_e32 v18, 2, v84
	v_lshlrev_b32_e32 v130, 2, v0
	v_mul_lo_u32 v194, v86, s86
	v_mul_lo_u32 v21, v86, 48
	v_and_or_b32 v22, v18, 3, v130
	v_add_u32_e32 v18, 0, v194
	v_lshlrev_b32_e32 v19, 1, v84
	v_add_u32_e32 v135, v18, v131
	v_add_u32_e32 v18, v18, v21
	s_movk_i32 s8, 0xffd0
	v_and_b32_e32 v20, 32, v19
	v_mad_u32_u24 v19, v85, s86, 0
	v_lshlrev_b32_e32 v195, 4, v0
	v_add_u32_e32 v134, v18, v131
	v_add_u32_e32 v42, v19, v195
	v_mad_u64_u32 v[18:19], s[8:9], v86, s8, v[134:135]
	v_add_u32_e32 v19, v18, v21
	s_waitcnt vmcnt(7)
	ds_write_b128 v135, v[2:5]
	s_waitcnt vmcnt(6)
	ds_write_b128 v134, v[6:9] offset:9216
	s_waitcnt vmcnt(5)
	ds_write_b128 v18, v[10:13] offset:21504
	s_waitcnt vmcnt(4)
	ds_write_b128 v19, v[14:17] offset:30720
	v_mov_b32_e32 v242, 0x1affc
	v_mov_b32_e32 v243, 0xf149f2ca
	ds_write_b32 v242, v243
	s_waitcnt lgkmcnt(0)
	s_barrier
	ds_read_b128 v[2:5], v42
	ds_read_b128 v[34:37], v42 offset:32
	ds_read_b128 v[6:9], v42 offset:4608
	ds_read_b128 v[38:41], v42 offset:4640
	ds_read_b128 v[44:47], v42 offset:64
	ds_read_b128 v[48:51], v42 offset:96
	ds_read_b128 v[52:55], v42 offset:4672
	ds_read_b128 v[56:59], v42 offset:4704
	v_lshlrev_b32_e32 v10, 3, v84
	v_and_b32_e32 v10, 24, v10
	v_mul_lo_u32 v11, v22, s85
	v_or3_b32 v196, v11, v20, v10
	s_waitcnt vmcnt(3) lgkmcnt(7)
	v_mfma_f32_32x32x16_bf16 v[18:33], v[2:5], v[98:101], 0
	s_waitcnt lgkmcnt(5)
	v_mfma_f32_32x32x16_bf16 v[2:17], v[6:9], v[98:101], 0
	s_waitcnt vmcnt(2)
	v_mfma_f32_32x32x16_bf16 v[18:33], v[34:37], v[102:105], v[18:33]
	s_waitcnt lgkmcnt(4)
	v_mfma_f32_32x32x16_bf16 v[2:17], v[38:41], v[102:105], v[2:17]
	s_waitcnt vmcnt(1) lgkmcnt(3)
	v_mfma_f32_32x32x16_bf16 v[18:33], v[44:47], v[106:109], v[18:33]
	v_add_u32_e32 v89, 0, v196
	ds_read_b64_tr_b16 v[34:35], v89 offset:9216
	ds_read_b64_tr_b16 v[36:37], v89 offset:10752
	ds_read_b64_tr_b16 v[40:41], v89 offset:10816
	ds_read_b64_tr_b16 v[38:39], v89 offset:9280
	v_subrev_u32_e32 v88, 31, v193
	v_lshlrev_b32_e32 v45, 6, v0
	v_sub_u32_e32 v46, v88, v45
	v_cmp_lt_i32_e32 vcc, -1, v46
	v_cmp_gt_i32_e64 s[8:9], 32, v0
	s_waitcnt lgkmcnt(5)
	v_mfma_f32_32x32x16_bf16 v[2:17], v[52:55], v[106:109], v[2:17]
	s_and_b64 s[10:11], s[8:9], vcc
	v_mov_b32_e32 v43, 0xf149f2ca
	v_mov_b32_e32 v44, 0xf149f2ca
	s_waitcnt vmcnt(0)
	v_mfma_f32_32x32x16_bf16 v[18:33], v[48:51], v[110:113], v[18:33]
	s_waitcnt lgkmcnt(4)
	v_mfma_f32_32x32x16_bf16 v[2:17], v[56:59], v[110:113], v[2:17]
	v_min_u32_e32 v210, 0x7f, v46
	v_lshl_add_u32 v210, v210, 2, s3
	v_cndmask_b32_e64 v210, v242, v210, s[10:11]
	ds_read_b32 v210, v210
	v_sub_u32_e32 v74, v193, v45
	v_add_u32_e32 v150, 0xfffffde1, v74
	v_cmp_lt_i32_e64 s[8:9], -1, v150
	v_cmp_gt_i32_e32 vcc, 24, v0
	s_and_b64 s[10:11], vcc, s[8:9]
	v_min_u32_e32 v211, 0x7f, v150
	v_lshl_add_u32 v211, v211, 2, s3
	v_cndmask_b32_e64 v211, v242, v211, s[10:11]
	ds_read_b32 v211, v211
	v_or_b32_e32 v151, 1, v130
	v_lshlrev_b32_e32 v152, 4, v151
	v_sub_u32_e32 v45, v88, v152
	v_cmp_lt_i32_e64 s[8:9], -1, v45
	v_cmp_gt_i32_e64 s[10:11], s82, v151
	s_and_b64 s[10:11], s[10:11], s[8:9]
	v_min_u32_e32 v212, 0x7f, v45
	v_lshl_add_u32 v212, v212, 2, s3
	v_cndmask_b32_e64 v212, v242, v212, s[10:11]
	ds_read_b32 v212, v212
	v_add_u32_e32 v153, 0xfffffdd1, v74
	v_cmp_lt_i32_e64 s[8:9], -1, v153
	s_and_b64 s[10:11], vcc, s[8:9]
	v_min_u32_e32 v213, 0x7f, v153
	v_lshl_add_u32 v213, v213, 2, s3
	v_cndmask_b32_e64 v213, v242, v213, s[10:11]
	ds_read_b32 v213, v213
	v_or_b32_e32 v154, 2, v130
	v_lshlrev_b32_e32 v155, 4, v154
	v_sub_u32_e32 v45, v88, v155
	v_cmp_lt_i32_e64 s[8:9], -1, v45
	v_cmp_gt_i32_e64 s[10:11], s82, v154
	s_and_b64 s[10:11], s[10:11], s[8:9]
	v_min_u32_e32 v214, 0x7f, v45
	v_lshl_add_u32 v214, v214, 2, s3
	v_cndmask_b32_e64 v214, v242, v214, s[10:11]
	ds_read_b32 v214, v214
	v_add_u32_e32 v156, 0xfffffdc1, v74
	v_cmp_lt_i32_e64 s[8:9], -1, v156
	s_and_b64 s[10:11], vcc, s[8:9]
	v_min_u32_e32 v215, 0x7f, v156
	v_lshl_add_u32 v215, v215, 2, s3
	v_cndmask_b32_e64 v215, v242, v215, s[10:11]
	ds_read_b32 v215, v215
	v_or_b32_e32 v157, 3, v130
	v_lshlrev_b32_e32 v158, 4, v157
	v_sub_u32_e32 v45, v88, v158
	v_cmp_lt_i32_e32 vcc, -1, v45
	v_cmp_gt_i32_e64 s[8:9], s82, v157
	s_and_b64 s[10:11], s[8:9], vcc
	v_min_u32_e32 v216, 0x7f, v45
	v_lshl_add_u32 v216, v216, 2, s3
	v_cndmask_b32_e64 v216, v242, v216, s[10:11]
	ds_read_b32 v216, v216
	v_add_u32_e32 v159, 0xfffffdb1, v74
	v_cmp_lt_i32_e32 vcc, -1, v159
	v_cmp_gt_i32_e64 s[8:9], 23, v0
	s_and_b64 s[10:11], s[8:9], vcc
	v_min_u32_e32 v217, 0x7f, v159
	v_lshl_add_u32 v217, v217, 2, s3
	v_cndmask_b32_e64 v217, v242, v217, s[10:11]
	ds_read_b32 v217, v217
	v_add_u32_e32 v45, 0xffffff61, v74
	v_cmp_lt_i32_e64 s[8:9], -1, v45
	v_cmp_gt_i32_e32 vcc, 30, v0
	s_and_b64 s[10:11], vcc, s[8:9]
	v_min_u32_e32 v218, 0x7f, v45
	v_lshl_add_u32 v218, v218, 2, s3
	v_cndmask_b32_e64 v218, v242, v218, s[10:11]
	ds_read_b32 v218, v218
	v_add_u32_e32 v160, 0xfffffd61, v74
	v_cmp_lt_i32_e64 s[10:11], -1, v160
	v_cmp_gt_i32_e64 s[8:9], 22, v0
	s_and_b64 s[12:13], s[8:9], s[10:11]
	v_min_u32_e32 v219, 0x7f, v160
	v_lshl_add_u32 v219, v219, 2, s3
	v_cndmask_b32_e64 v219, v242, v219, s[12:13]
	ds_read_b32 v219, v219
	v_add_u32_e32 v45, 0xffffff51, v74
	v_cmp_lt_i32_e64 s[10:11], -1, v45
	s_and_b64 s[12:13], vcc, s[10:11]
	v_min_u32_e32 v220, 0x7f, v45
	v_lshl_add_u32 v220, v220, 2, s3
	v_cndmask_b32_e64 v220, v242, v220, s[12:13]
	ds_read_b32 v220, v220
	v_add_u32_e32 v161, 0xfffffd51, v74
	v_cmp_lt_i32_e64 s[10:11], -1, v161
	s_and_b64 s[12:13], s[8:9], s[10:11]
	v_min_u32_e32 v221, 0x7f, v161
	v_lshl_add_u32 v221, v221, 2, s3
	v_cndmask_b32_e64 v221, v242, v221, s[12:13]
	ds_read_b32 v221, v221
	v_add_u32_e32 v45, 0xffffff41, v74
	v_cmp_lt_i32_e64 s[10:11], -1, v45
	s_and_b64 s[12:13], vcc, s[10:11]
	v_min_u32_e32 v222, 0x7f, v45
	v_lshl_add_u32 v222, v222, 2, s3
	v_cndmask_b32_e64 v222, v242, v222, s[12:13]
	ds_read_b32 v222, v222
	v_add_u32_e32 v162, 0xfffffd41, v74
	v_cmp_lt_i32_e32 vcc, -1, v162
	s_and_b64 s[10:11], s[8:9], vcc
	v_min_u32_e32 v223, 0x7f, v162
	v_lshl_add_u32 v223, v223, 2, s3
	v_cndmask_b32_e64 v223, v242, v223, s[10:11]
	ds_read_b32 v223, v223
	v_add_u32_e32 v45, 0xffffff31, v74
	v_cmp_lt_i32_e32 vcc, -1, v45
	v_cmp_gt_i32_e64 s[8:9], 29, v0
	s_and_b64 s[10:11], s[8:9], vcc
	v_min_u32_e32 v224, 0x7f, v45
	v_lshl_add_u32 v224, v224, 2, s3
	v_cndmask_b32_e64 v224, v242, v224, s[10:11]
	ds_read_b32 v224, v224
	v_add_u32_e32 v163, 0xfffffd31, v74
	v_cmp_lt_i32_e32 vcc, -1, v163
	v_cmp_gt_i32_e64 s[8:9], 21, v0
	s_and_b64 s[10:11], s[8:9], vcc
	v_min_u32_e32 v225, 0x7f, v163
	v_lshl_add_u32 v225, v225, 2, s3
	v_cndmask_b32_e64 v225, v242, v225, s[10:11]
	ds_read_b32 v225, v225
	v_add_u32_e32 v45, 0xfffffee1, v74
	v_cmp_lt_i32_e64 s[8:9], -1, v45
	v_cmp_gt_i32_e32 vcc, 28, v0
	s_and_b64 s[10:11], vcc, s[8:9]
	v_min_u32_e32 v226, 0x7f, v45
	v_lshl_add_u32 v226, v226, 2, s3
	v_cndmask_b32_e64 v226, v242, v226, s[10:11]
	ds_read_b32 v226, v226
	v_add_u32_e32 v164, 0xfffffce1, v74
	v_cmp_lt_i32_e64 s[10:11], -1, v164
	v_cmp_gt_i32_e64 s[8:9], 20, v0
	s_and_b64 s[12:13], s[8:9], s[10:11]
	v_min_u32_e32 v227, 0x7f, v164
	v_lshl_add_u32 v227, v227, 2, s3
	v_cndmask_b32_e64 v227, v242, v227, s[12:13]
	ds_read_b32 v227, v227
	v_add_u32_e32 v45, 0xfffffed1, v74
	v_cmp_lt_i32_e64 s[10:11], -1, v45
	s_and_b64 s[12:13], vcc, s[10:11]
	v_min_u32_e32 v228, 0x7f, v45
	v_lshl_add_u32 v228, v228, 2, s3
	v_cndmask_b32_e64 v228, v242, v228, s[12:13]
	ds_read_b32 v228, v228
	v_add_u32_e32 v165, 0xfffffcd1, v74
	v_cmp_lt_i32_e64 s[10:11], -1, v165
	s_and_b64 s[12:13], s[8:9], s[10:11]
	v_min_u32_e32 v229, 0x7f, v165
	v_lshl_add_u32 v229, v229, 2, s3
	v_cndmask_b32_e64 v229, v242, v229, s[12:13]
	ds_read_b32 v229, v229
	v_add_u32_e32 v45, 0xfffffec1, v74
	v_cmp_lt_i32_e64 s[10:11], -1, v45
	s_and_b64 s[12:13], vcc, s[10:11]
	v_min_u32_e32 v230, 0x7f, v45
	v_lshl_add_u32 v230, v230, 2, s3
	v_cndmask_b32_e64 v230, v242, v230, s[12:13]
	ds_read_b32 v230, v230
	v_add_u32_e32 v166, 0xfffffcc1, v74
	v_cmp_lt_i32_e32 vcc, -1, v166
	s_and_b64 s[10:11], s[8:9], vcc
	v_min_u32_e32 v231, 0x7f, v166
	v_lshl_add_u32 v231, v231, 2, s3
	v_cndmask_b32_e64 v231, v242, v231, s[10:11]
	ds_read_b32 v231, v231
	v_add_u32_e32 v45, 0xfffffeb1, v74
	v_cmp_lt_i32_e32 vcc, -1, v45
	v_cmp_gt_i32_e64 s[8:9], 27, v0
	s_and_b64 s[10:11], s[8:9], vcc
	v_min_u32_e32 v232, 0x7f, v45
	v_lshl_add_u32 v232, v232, 2, s3
	v_cndmask_b32_e64 v232, v242, v232, s[10:11]
	ds_read_b32 v232, v232
	v_add_u32_e32 v167, 0xfffffcb1, v74
	v_cmp_lt_i32_e32 vcc, -1, v167
	v_cmp_gt_i32_e64 s[8:9], 19, v0
	s_and_b64 s[10:11], s[8:9], vcc
	v_min_u32_e32 v233, 0x7f, v167
	v_lshl_add_u32 v233, v233, 2, s3
	v_cndmask_b32_e64 v233, v242, v233, s[10:11]
	ds_read_b32 v233, v233
	v_add_u32_e32 v45, 0xfffffe61, v74
	v_cmp_lt_i32_e64 s[8:9], -1, v45
	v_cmp_gt_i32_e32 vcc, 26, v0
	s_and_b64 s[10:11], vcc, s[8:9]
	v_min_u32_e32 v234, 0x7f, v45
	v_lshl_add_u32 v234, v234, 2, s3
	v_cndmask_b32_e64 v234, v242, v234, s[10:11]
	ds_read_b32 v234, v234
	v_add_u32_e32 v168, 0xfffffc61, v74
	v_cmp_lt_i32_e64 s[10:11], -1, v168
	v_cmp_gt_i32_e64 s[8:9], 18, v0
	s_and_b64 s[12:13], s[8:9], s[10:11]
	v_min_u32_e32 v235, 0x7f, v168
	v_lshl_add_u32 v235, v235, 2, s3
	v_cndmask_b32_e64 v235, v242, v235, s[12:13]
	ds_read_b32 v235, v235
	v_add_u32_e32 v45, 0xfffffe51, v74
	v_cmp_lt_i32_e64 s[10:11], -1, v45
	s_and_b64 s[12:13], vcc, s[10:11]
	v_min_u32_e32 v236, 0x7f, v45
	v_lshl_add_u32 v236, v236, 2, s3
	v_cndmask_b32_e64 v236, v242, v236, s[12:13]
	ds_read_b32 v236, v236
	v_add_u32_e32 v169, 0xfffffc51, v74
	v_cmp_lt_i32_e64 s[10:11], -1, v169
	s_and_b64 s[12:13], s[8:9], s[10:11]
	v_min_u32_e32 v237, 0x7f, v169
	v_lshl_add_u32 v237, v237, 2, s3
	v_cndmask_b32_e64 v237, v242, v237, s[12:13]
	ds_read_b32 v237, v237
	v_add_u32_e32 v45, 0xfffffe41, v74
	v_cmp_lt_i32_e64 s[10:11], -1, v45
	s_and_b64 s[12:13], vcc, s[10:11]
	v_min_u32_e32 v238, 0x7f, v45
	v_lshl_add_u32 v238, v238, 2, s3
	v_cndmask_b32_e64 v238, v242, v238, s[12:13]
	ds_read_b32 v238, v238
	v_add_u32_e32 v170, 0xfffffc41, v74
	v_cmp_lt_i32_e32 vcc, -1, v170
	s_and_b64 s[10:11], s[8:9], vcc
	v_min_u32_e32 v239, 0x7f, v170
	v_lshl_add_u32 v239, v239, 2, s3
	v_cndmask_b32_e64 v239, v242, v239, s[10:11]
	ds_read_b32 v239, v239
	v_add_u32_e32 v45, 0xfffffe31, v74
	v_cmp_lt_i32_e32 vcc, -1, v45
	v_cmp_gt_i32_e64 s[8:9], 25, v0
	s_and_b64 s[10:11], s[8:9], vcc
	v_min_u32_e32 v240, 0x7f, v45
	v_lshl_add_u32 v240, v240, 2, s3
	v_cndmask_b32_e64 v240, v242, v240, s[10:11]
	ds_read_b32 v240, v240
	v_add_u32_e32 v171, 0xfffffc31, v74
	v_cmp_lt_i32_e32 vcc, -1, v171
	v_cmp_gt_i32_e64 s[8:9], 17, v0
	s_and_b64 s[10:11], s[8:9], vcc
	v_min_u32_e32 v241, 0x7f, v171
	v_lshl_add_u32 v241, v241, 2, s3
	v_cndmask_b32_e64 v241, v242, v241, s[10:11]
	ds_read_b32 v241, v241
	s_waitcnt lgkmcnt(0)
	v_add_f32_e32 v44, v18, v210
	v_add_f32_e32 v43, v2, v211
	v_add_f32_e32 v18, v19, v212
	v_add_f32_e32 v2, v3, v213
	v_add_f32_e32 v19, v20, v214
	v_add_f32_e32 v3, v4, v215
	v_add_f32_e32 v20, v21, v216
	v_add_f32_e32 v4, v5, v217
	v_add_f32_e32 v21, v22, v218
	v_add_f32_e32 v5, v6, v219
	v_add_f32_e32 v22, v23, v220
	v_add_f32_e32 v6, v7, v221
	v_add_f32_e32 v23, v24, v222
	v_add_f32_e32 v7, v8, v223
	v_add_f32_e32 v24, v25, v224
	v_add_f32_e32 v8, v9, v225
	v_add_f32_e32 v25, v26, v226
	v_add_f32_e32 v9, v10, v227
	v_add_f32_e32 v26, v27, v228
	v_add_f32_e32 v10, v11, v229
	v_add_f32_e32 v27, v28, v230
	v_add_f32_e32 v11, v12, v231
	v_add_f32_e32 v28, v29, v232
	v_add_f32_e32 v12, v13, v233
	v_add_f32_e32 v29, v30, v234
	v_add_f32_e32 v13, v14, v235
	v_add_f32_e32 v30, v31, v236
	v_add_f32_e32 v14, v15, v237
	v_add_f32_e32 v31, v32, v238
	v_add_f32_e32 v15, v16, v239
	v_add_f32_e32 v32, v33, v240
	v_add_f32_e32 v16, v17, v241
	v_max3_f32 v17, v191, v44, v43
	v_lshlrev_b32_e32 v33, 7, v0
	v_max3_f32 v17, v17, v18, v2
	v_lshlrev_b32_e32 v45, 2, v85
	v_max3_f32 v17, v17, v19, v3
	s_movk_i32 s8, 0x80
	v_max3_f32 v17, v17, v20, v4
	v_bitop3_b32 v197, v33, s8, v45 bitop3:0x36
	v_max3_f32 v17, v17, v21, v5
	v_mov_b32_e32 v79, 0xf149f2ca
	v_max3_f32 v17, v17, v22, v6
	v_max3_f32 v17, v17, v23, v7
	v_max3_f32 v17, v17, v24, v8
	v_max3_f32 v17, v17, v25, v9
	v_max3_f32 v17, v17, v26, v10
	v_max3_f32 v17, v17, v27, v11
	v_max3_f32 v17, v17, v28, v12
	v_max3_f32 v17, v17, v29, v13
	v_max3_f32 v17, v17, v30, v14
	v_max3_f32 v17, v17, v31, v15
	v_max3_f32 v17, v17, v32, v16
	ds_bpermute_b32 v33, v197, v17
	v_max_f32_e32 v17, v17, v17
	s_waitcnt lgkmcnt(0)
	v_max_f32_e32 v33, v33, v33
	v_max_f32_e32 v17, v17, v33
	v_max_f32_e32 v75, 0xf149f2ca, v17
	v_sub_f32_e32 v5, v5, v75
	v_exp_f32_e32 v59, v5
	v_sub_f32_e32 v5, v22, v75
	v_exp_f32_e32 v22, v5
	v_sub_f32_e32 v5, v6, v75
	v_exp_f32_e32 v60, v5
	v_sub_f32_e32 v5, v23, v75
	v_exp_f32_e32 v23, v5
	v_sub_f32_e32 v5, v7, v75
	v_sub_f32_e32 v33, v44, v75
	v_sub_f32_e32 v43, v43, v75
	v_exp_f32_e32 v61, v5
	v_sub_f32_e32 v5, v24, v75
	v_exp_f32_e32 v33, v33
	v_exp_f32_e32 v43, v43
	v_sub_f32_e32 v18, v18, v75
	v_sub_f32_e32 v2, v2, v75
	v_sub_f32_e32 v3, v3, v75
	v_exp_f32_e32 v24, v5
	v_sub_f32_e32 v5, v8, v75
	v_exp_f32_e32 v18, v18
	v_exp_f32_e32 v56, v2
	v_sub_f32_e32 v19, v19, v75
	v_exp_f32_e32 v57, v3
	v_sub_f32_e32 v3, v20, v75
	v_exp_f32_e32 v62, v5
	v_sub_f32_e32 v5, v25, v75
	v_exp_f32_e32 v19, v19
	v_exp_f32_e32 v20, v3
	v_sub_f32_e32 v3, v4, v75
	v_exp_f32_e32 v63, v5
	v_sub_f32_e32 v5, v9, v75
	v_exp_f32_e32 v58, v3
	v_sub_f32_e32 v21, v21, v75
	v_exp_f32_e32 v64, v5
	v_sub_f32_e32 v5, v26, v75
	v_add_f32_e32 v44, v33, v43
	v_exp_f32_e32 v21, v21
	v_exp_f32_e32 v65, v5
	v_sub_f32_e32 v5, v10, v75
	v_add_f32_e32 v44, 0, v44
	v_add_f32_e32 v45, v18, v56
	v_exp_f32_e32 v66, v5
	v_sub_f32_e32 v5, v27, v75
	v_add_f32_e32 v3, v45, v44
	v_add_f32_e32 v4, v19, v57
	v_exp_f32_e32 v67, v5
	v_sub_f32_e32 v5, v11, v75
	v_add_f32_e32 v3, v4, v3
	v_add_f32_e32 v4, v20, v58
	v_exp_f32_e32 v68, v5
	v_sub_f32_e32 v5, v28, v75
	v_add_f32_e32 v3, v4, v3
	v_add_f32_e32 v4, v21, v59
	v_exp_f32_e32 v69, v5
	v_sub_f32_e32 v5, v12, v75
	v_add_f32_e32 v3, v4, v3
	v_add_f32_e32 v4, v22, v60
	v_exp_f32_e32 v70, v5
	v_sub_f32_e32 v5, v29, v75
	v_add_f32_e32 v3, v4, v3
	v_add_f32_e32 v4, v23, v61
	v_exp_f32_e32 v71, v5
	v_sub_f32_e32 v5, v13, v75
	v_add_f32_e32 v3, v4, v3
	v_add_f32_e32 v4, v24, v62
	v_exp_f32_e32 v72, v5
	v_sub_f32_e32 v5, v30, v75
	v_add_f32_e32 v3, v4, v3
	v_add_f32_e32 v4, v63, v64
	v_exp_f32_e32 v73, v5
	v_sub_f32_e32 v5, v14, v75
	v_add_f32_e32 v3, v4, v3
	v_add_f32_e32 v4, v65, v66
	v_exp_f32_e32 v80, v5
	v_add_f32_e32 v3, v4, v3
	v_add_f32_e32 v4, v67, v68
	v_add_f32_e32 v3, v4, v3
	v_add_f32_e32 v4, v69, v70
	v_add_f32_e32 v3, v4, v3
	v_add_f32_e32 v4, v71, v72
	v_add_f32_e32 v3, v4, v3
	v_add_f32_e32 v4, v73, v80
	v_add_f32_e32 v3, v4, v3
	v_sub_f32_e32 v4, v31, v75
	v_exp_f32_e32 v81, v4
	v_sub_f32_e32 v4, v15, v75
	v_exp_f32_e32 v90, v4
	v_sub_f32_e32 v4, v32, v75
	v_exp_f32_e32 v91, v4
	v_sub_f32_e32 v4, v16, v75
	v_exp_f32_e32 v92, v4
	v_sub_f32_e32 v2, 0xf149f2ca, v75
	v_add_f32_e32 v4, v81, v90
	v_add_f32_e32 v3, v4, v3
	v_exp_f32_e32 v2, v2
	v_add_f32_e32 v4, v91, v92
	v_add_f32_e32 v76, v4, v3
	ds_bpermute_b32 v77, v197, v76
	v_cmp_gt_f32_e32 vcc, v17, v79
	s_cmp_lg_u64 vcc, 0
	v_mul_f32_e32 v78, 0, v2
	s_cselect_b64 vcc, -1, 0
	v_cndmask_b32_e32 v2, 0, v78, vcc
	v_mov_b32_e32 v3, v2
	v_mov_b32_e32 v4, v2
	v_mov_b32_e32 v5, v2
	v_mov_b32_e32 v6, v2
	v_mov_b32_e32 v7, v2
	v_mov_b32_e32 v8, v2
	v_mov_b32_e32 v9, v2
	v_mov_b32_e32 v10, v2
	v_mov_b32_e32 v11, v2
	v_mov_b32_e32 v12, v2
	v_mov_b32_e32 v13, v2
	v_mov_b32_e32 v14, v2
	v_mov_b32_e32 v15, v2
	v_mov_b32_e32 v16, v2
	v_mov_b32_e32 v17, v2
	ds_read_b64_tr_b16 v[44:45], v89 offset:12288
	ds_read_b64_tr_b16 v[46:47], v89 offset:13824
	ds_read_b64_tr_b16 v[50:51], v89 offset:13888
	ds_read_b64_tr_b16 v[48:49], v89 offset:12352
	v_cvt_pk_bf16_f32 v52, v33, v18
	v_cvt_pk_bf16_f32 v53, v19, v20
	v_cvt_pk_bf16_f32 v54, v21, v22
	v_cvt_pk_bf16_f32 v55, v23, v24
	s_nop 1
	v_mfma_f32_32x32x16_bf16 v[18:33], v[34:37], v[52:55], v[2:17]
	v_mfma_f32_32x32x16_bf16 v[2:17], v[38:41], v[52:55], v[2:17]
	ds_read_b64_tr_b16 v[34:35], v89 offset:15360
	ds_read_b64_tr_b16 v[36:37], v89 offset:16896
	ds_read_b64_tr_b16 v[40:41], v89 offset:16960
	ds_read_b64_tr_b16 v[38:39], v89 offset:15424
	v_cvt_pk_bf16_f32 v52, v63, v65
	v_cvt_pk_bf16_f32 v53, v67, v69
	v_cvt_pk_bf16_f32 v54, v71, v73
	v_cvt_pk_bf16_f32 v55, v81, v91
	s_waitcnt lgkmcnt(6)
	s_nop 0
	v_mfma_f32_32x32x16_bf16 v[18:33], v[44:47], v[52:55], v[18:33]
	s_waitcnt lgkmcnt(4)
	v_mfma_f32_32x32x16_bf16 v[2:17], v[48:51], v[52:55], v[2:17]
	ds_read_b64_tr_b16 v[44:45], v89 offset:18432
	ds_read_b64_tr_b16 v[46:47], v89 offset:19968
	ds_read_b64_tr_b16 v[50:51], v89 offset:20032
	ds_read_b64_tr_b16 v[48:49], v89 offset:18496
	v_cvt_pk_bf16_f32 v52, v43, v56
	v_cvt_pk_bf16_f32 v53, v57, v58
	v_cvt_pk_bf16_f32 v54, v59, v60
	v_cvt_pk_bf16_f32 v55, v61, v62
	s_waitcnt lgkmcnt(6)
	s_nop 0
	v_mfma_f32_32x32x16_bf16 v[18:33], v[34:37], v[52:55], v[18:33]
	s_waitcnt lgkmcnt(4)
	v_mfma_f32_32x32x16_bf16 v[2:17], v[38:41], v[52:55], v[2:17]
	v_cvt_pk_bf16_f32 v34, v64, v66
	v_cvt_pk_bf16_f32 v35, v68, v70
	v_cvt_pk_bf16_f32 v36, v72, v80
	v_cvt_pk_bf16_f32 v37, v90, v92
	s_waitcnt lgkmcnt(2)
	s_nop 0
	v_mfma_f32_32x32x16_bf16 v[18:33], v[44:47], v[34:37], v[18:33]
	s_waitcnt lgkmcnt(0)
	v_mfma_f32_32x32x16_bf16 v[2:17], v[48:51], v[34:37], v[2:17]
	ds_read_b128 v[34:37], v42 offset:21504
	ds_read_b128 v[66:69], v42 offset:21536
	ds_read_b128 v[38:41], v42 offset:26112
	ds_read_b128 v[70:73], v42 offset:26144
	ds_read_b128 v[90:93], v42 offset:21568
	ds_read_b128 v[94:97], v42 offset:21600
	ds_read_b128 v[114:117], v42 offset:26176
	ds_read_b128 v[118:121], v42 offset:26208
	s_waitcnt lgkmcnt(7)
	v_mfma_f32_32x32x16_bf16 v[50:65], v[34:37], v[98:101], 0
	s_waitcnt lgkmcnt(5)
	v_mfma_f32_32x32x16_bf16 v[34:49], v[38:41], v[98:101], 0
	v_mfma_f32_32x32x16_bf16 v[50:65], v[66:69], v[102:105], v[50:65]
	s_waitcnt lgkmcnt(4)
	v_mfma_f32_32x32x16_bf16 v[34:49], v[70:73], v[102:105], v[34:49]
	s_waitcnt lgkmcnt(3)
	v_mfma_f32_32x32x16_bf16 v[50:65], v[90:93], v[106:109], v[50:65]
	ds_read_b64_tr_b16 v[66:67], v89 offset:30720
	ds_read_b64_tr_b16 v[68:69], v89 offset:32256
	ds_read_b64_tr_b16 v[72:73], v89 offset:32320
	ds_read_b64_tr_b16 v[70:71], v89 offset:30784
	v_add_u32_e32 v81, 0xfffffbe1, v74
	v_cmp_lt_i32_e64 s[8:9], -1, v81
	v_cmp_gt_i32_e32 vcc, 16, v0
	s_and_b64 s[10:11], vcc, s[8:9]
	v_mov_b32_e32 v80, 0xf149f2ca
	s_waitcnt lgkmcnt(5)
	v_mfma_f32_32x32x16_bf16 v[34:49], v[114:117], v[106:109], v[34:49]
	v_mfma_f32_32x32x16_bf16 v[50:65], v[94:97], v[110:113], v[50:65]
	s_waitcnt lgkmcnt(4)
	v_mfma_f32_32x32x16_bf16 v[34:49], v[118:121], v[110:113], v[34:49]
	v_min_u32_e32 v210, 0x7f, v81
	v_lshl_add_u32 v210, v210, 2, s3
	v_cndmask_b32_e64 v210, v242, v210, s[10:11]
	ds_read_b32 v210, v210
	s_nop 6
	v_add_u32_e32 v150, 0xfffff9e1, v74
	v_cmp_lt_i32_e64 s[10:11], -1, v150
	v_cmp_gt_i32_e64 s[8:9], 8, v0
	s_and_b64 s[12:13], s[8:9], s[10:11]
	v_min_u32_e32 v211, 0x7f, v150
	v_lshl_add_u32 v211, v211, 2, s3
	v_cndmask_b32_e64 v211, v242, v211, s[12:13]
	ds_read_b32 v211, v211
	v_add_u32_e32 v81, 0xfffffbd1, v74
	v_cmp_lt_i32_e64 s[10:11], -1, v81
	s_and_b64 s[12:13], vcc, s[10:11]
	v_min_u32_e32 v212, 0x7f, v81
	v_lshl_add_u32 v212, v212, 2, s3
	v_cndmask_b32_e64 v212, v242, v212, s[12:13]
	ds_read_b32 v212, v212
	v_add_u32_e32 v151, 0xfffff9d1, v74
	v_cmp_lt_i32_e64 s[10:11], -1, v151
	s_and_b64 s[12:13], s[8:9], s[10:11]
	v_min_u32_e32 v213, 0x7f, v151
	v_lshl_add_u32 v213, v213, 2, s3
	v_cndmask_b32_e64 v213, v242, v213, s[12:13]
	ds_read_b32 v213, v213
	v_add_u32_e32 v81, 0xfffffbc1, v74
	v_cmp_lt_i32_e64 s[10:11], -1, v81
	s_and_b64 s[12:13], vcc, s[10:11]
	v_min_u32_e32 v214, 0x7f, v81
	v_lshl_add_u32 v214, v214, 2, s3
	v_cndmask_b32_e64 v214, v242, v214, s[12:13]
	ds_read_b32 v214, v214
	v_add_u32_e32 v152, 0xfffff9c1, v74
	v_cmp_lt_i32_e32 vcc, -1, v152
	s_and_b64 s[10:11], s[8:9], vcc
	v_min_u32_e32 v215, 0x7f, v152
	v_lshl_add_u32 v215, v215, 2, s3
	v_cndmask_b32_e64 v215, v242, v215, s[10:11]
	ds_read_b32 v215, v215
	v_add_u32_e32 v81, 0xfffffbb1, v74
	v_cmp_lt_i32_e32 vcc, -1, v81
	v_cmp_gt_i32_e64 s[8:9], 15, v0
	s_and_b64 s[10:11], s[8:9], vcc
	v_min_u32_e32 v216, 0x7f, v81
	v_lshl_add_u32 v216, v216, 2, s3
	v_cndmask_b32_e64 v216, v242, v216, s[10:11]
	ds_read_b32 v216, v216
	v_add_u32_e32 v153, 0xfffff9b1, v74
	v_cmp_lt_i32_e32 vcc, -1, v153
	v_cmp_gt_i32_e64 s[8:9], 7, v0
	s_and_b64 s[10:11], s[8:9], vcc
	v_min_u32_e32 v217, 0x7f, v153
	v_lshl_add_u32 v217, v217, 2, s3
	v_cndmask_b32_e64 v217, v242, v217, s[10:11]
	ds_read_b32 v217, v217
	v_add_u32_e32 v81, 0xfffffb61, v74
	v_cmp_lt_i32_e64 s[8:9], -1, v81
	v_cmp_gt_i32_e32 vcc, 14, v0
	s_and_b64 s[10:11], vcc, s[8:9]
	v_min_u32_e32 v218, 0x7f, v81
	v_lshl_add_u32 v218, v218, 2, s3
	v_cndmask_b32_e64 v218, v242, v218, s[10:11]
	ds_read_b32 v218, v218
	v_add_u32_e32 v154, 0xfffff961, v74
	v_cmp_lt_i32_e64 s[10:11], -1, v154
	v_cmp_gt_i32_e64 s[8:9], 6, v0
	s_and_b64 s[12:13], s[8:9], s[10:11]
	v_min_u32_e32 v219, 0x7f, v154
	v_lshl_add_u32 v219, v219, 2, s3
	v_cndmask_b32_e64 v219, v242, v219, s[12:13]
	ds_read_b32 v219, v219
	v_add_u32_e32 v81, 0xfffffb51, v74
	v_cmp_lt_i32_e64 s[10:11], -1, v81
	s_and_b64 s[12:13], vcc, s[10:11]
	v_min_u32_e32 v220, 0x7f, v81
	v_lshl_add_u32 v220, v220, 2, s3
	v_cndmask_b32_e64 v220, v242, v220, s[12:13]
	ds_read_b32 v220, v220
	v_add_u32_e32 v155, 0xfffff951, v74
	v_cmp_lt_i32_e64 s[10:11], -1, v155
	s_and_b64 s[12:13], s[8:9], s[10:11]
	v_min_u32_e32 v221, 0x7f, v155
	v_lshl_add_u32 v221, v221, 2, s3
	v_cndmask_b32_e64 v221, v242, v221, s[12:13]
	ds_read_b32 v221, v221
	v_add_u32_e32 v81, 0xfffffb41, v74
	v_cmp_lt_i32_e64 s[10:11], -1, v81
	s_and_b64 s[12:13], vcc, s[10:11]
	v_min_u32_e32 v222, 0x7f, v81
	v_lshl_add_u32 v222, v222, 2, s3
	v_cndmask_b32_e64 v222, v242, v222, s[12:13]
	ds_read_b32 v222, v222
	v_add_u32_e32 v156, 0xfffff941, v74
	v_cmp_lt_i32_e32 vcc, -1, v156
	s_and_b64 s[10:11], s[8:9], vcc
	v_min_u32_e32 v223, 0x7f, v156
	v_lshl_add_u32 v223, v223, 2, s3
	v_cndmask_b32_e64 v223, v242, v223, s[10:11]
	ds_read_b32 v223, v223
	v_add_u32_e32 v81, 0xfffffb31, v74
	v_cmp_lt_i32_e32 vcc, -1, v81
	v_cmp_gt_i32_e64 s[8:9], 13, v0
	s_and_b64 s[10:11], s[8:9], vcc
	v_min_u32_e32 v224, 0x7f, v81
	v_lshl_add_u32 v224, v224, 2, s3
	v_cndmask_b32_e64 v224, v242, v224, s[10:11]
	ds_read_b32 v224, v224
	v_add_u32_e32 v157, 0xfffff931, v74
	v_cmp_lt_i32_e32 vcc, -1, v157
	v_cmp_gt_i32_e64 s[8:9], 5, v0
	s_and_b64 s[10:11], s[8:9], vcc
	v_min_u32_e32 v225, 0x7f, v157
	v_lshl_add_u32 v225, v225, 2, s3
	v_cndmask_b32_e64 v225, v242, v225, s[10:11]
	ds_read_b32 v225, v225
	v_add_u32_e32 v81, 0xfffffae1, v74
	v_cmp_lt_i32_e64 s[8:9], -1, v81
	v_cmp_gt_i32_e32 vcc, 12, v0
	s_and_b64 s[10:11], vcc, s[8:9]
	v_min_u32_e32 v226, 0x7f, v81
	v_lshl_add_u32 v226, v226, 2, s3
	v_cndmask_b32_e64 v226, v242, v226, s[10:11]
	ds_read_b32 v226, v226
	v_add_u32_e32 v158, 0xfffff8e1, v74
	v_cmp_lt_i32_e64 s[10:11], -1, v158
	v_cmp_gt_i32_e64 s[8:9], 4, v0
	s_and_b64 s[12:13], s[8:9], s[10:11]
	v_min_u32_e32 v227, 0x7f, v158
	v_lshl_add_u32 v227, v227, 2, s3
	v_cndmask_b32_e64 v227, v242, v227, s[12:13]
	ds_read_b32 v227, v227
	v_add_u32_e32 v81, 0xfffffad1, v74
	v_cmp_lt_i32_e64 s[10:11], -1, v81
	s_and_b64 s[12:13], vcc, s[10:11]
	v_min_u32_e32 v228, 0x7f, v81
	v_lshl_add_u32 v228, v228, 2, s3
	v_cndmask_b32_e64 v228, v242, v228, s[12:13]
	ds_read_b32 v228, v228
	v_add_u32_e32 v159, 0xfffff8d1, v74
	v_cmp_lt_i32_e64 s[10:11], -1, v159
	s_and_b64 s[12:13], s[8:9], s[10:11]
	v_min_u32_e32 v229, 0x7f, v159
	v_lshl_add_u32 v229, v229, 2, s3
	v_cndmask_b32_e64 v229, v242, v229, s[12:13]
	ds_read_b32 v229, v229
	v_add_u32_e32 v81, 0xfffffac1, v74
	v_cmp_lt_i32_e64 s[10:11], -1, v81
	s_and_b64 s[12:13], vcc, s[10:11]
	v_min_u32_e32 v230, 0x7f, v81
	v_lshl_add_u32 v230, v230, 2, s3
	v_cndmask_b32_e64 v230, v242, v230, s[12:13]
	ds_read_b32 v230, v230
	v_add_u32_e32 v160, 0xfffff8c1, v74
	v_cmp_lt_i32_e32 vcc, -1, v160
	s_and_b64 s[10:11], s[8:9], vcc
	v_min_u32_e32 v231, 0x7f, v160
	v_lshl_add_u32 v231, v231, 2, s3
	v_cndmask_b32_e64 v231, v242, v231, s[10:11]
	ds_read_b32 v231, v231
	v_add_u32_e32 v81, 0xfffffab1, v74
	v_cmp_lt_i32_e32 vcc, -1, v81
	v_cmp_gt_i32_e64 s[8:9], 11, v0
	s_and_b64 s[10:11], s[8:9], vcc
	v_min_u32_e32 v232, 0x7f, v81
	v_lshl_add_u32 v232, v232, 2, s3
	v_cndmask_b32_e64 v232, v242, v232, s[10:11]
	ds_read_b32 v232, v232
	v_add_u32_e32 v161, 0xfffff8b1, v74
	v_cmp_lt_i32_e32 vcc, -1, v161
	v_cmp_gt_i32_e64 s[8:9], 3, v0
	s_and_b64 s[10:11], s[8:9], vcc
	v_min_u32_e32 v233, 0x7f, v161
	v_lshl_add_u32 v233, v233, 2, s3
	v_cndmask_b32_e64 v233, v242, v233, s[10:11]
	ds_read_b32 v233, v233
	v_add_u32_e32 v81, 0xfffffa61, v74
	v_cmp_lt_i32_e64 s[8:9], -1, v81
	v_cmp_gt_i32_e32 vcc, 10, v0
	s_and_b64 s[10:11], vcc, s[8:9]
	v_min_u32_e32 v234, 0x7f, v81
	v_lshl_add_u32 v234, v234, 2, s3
	v_cndmask_b32_e64 v234, v242, v234, s[10:11]
	ds_read_b32 v234, v234
	v_add_u32_e32 v162, 0xfffff861, v74
	v_cmp_lt_i32_e64 s[10:11], -1, v162
	v_cmp_gt_i32_e64 s[8:9], 2, v0
	s_and_b64 s[12:13], s[8:9], s[10:11]
	v_min_u32_e32 v235, 0x7f, v162
	v_lshl_add_u32 v235, v235, 2, s3
	v_cndmask_b32_e64 v235, v242, v235, s[12:13]
	ds_read_b32 v235, v235
	v_add_u32_e32 v81, 0xfffffa51, v74
	v_cmp_lt_i32_e64 s[10:11], -1, v81
	s_and_b64 s[12:13], vcc, s[10:11]
	v_min_u32_e32 v236, 0x7f, v81
	v_lshl_add_u32 v236, v236, 2, s3
	v_cndmask_b32_e64 v236, v242, v236, s[12:13]
	ds_read_b32 v236, v236
	v_add_u32_e32 v163, 0xfffff851, v74
	v_cmp_lt_i32_e64 s[10:11], -1, v163
	s_and_b64 s[12:13], s[8:9], s[10:11]
	v_min_u32_e32 v237, 0x7f, v163
	v_lshl_add_u32 v237, v237, 2, s3
	v_cndmask_b32_e64 v237, v242, v237, s[12:13]
	ds_read_b32 v237, v237
	v_add_u32_e32 v81, 0xfffffa41, v74
	v_cmp_lt_i32_e64 s[10:11], -1, v81
	s_and_b64 s[12:13], vcc, s[10:11]
	v_min_u32_e32 v238, 0x7f, v81
	v_lshl_add_u32 v238, v238, 2, s3
	v_cndmask_b32_e64 v238, v242, v238, s[12:13]
	ds_read_b32 v238, v238
	v_add_u32_e32 v164, 0xfffff841, v74
	v_cmp_lt_i32_e32 vcc, -1, v164
	s_and_b64 s[10:11], s[8:9], vcc
	v_min_u32_e32 v239, 0x7f, v164
	v_lshl_add_u32 v239, v239, 2, s3
	v_cndmask_b32_e64 v239, v242, v239, s[10:11]
	ds_read_b32 v239, v239
	v_add_u32_e32 v81, 0xfffffa31, v74
	v_cmp_lt_i32_e32 vcc, -1, v81
	v_cmp_gt_i32_e64 s[8:9], 9, v0
	s_and_b64 s[10:11], s[8:9], vcc
	v_min_u32_e32 v240, 0x7f, v81
	v_lshl_add_u32 v240, v240, 2, s3
	v_cndmask_b32_e64 v240, v242, v240, s[10:11]
	ds_read_b32 v240, v240
	v_add_u32_e32 v165, 0xfffff831, v74
	v_cmp_lt_i32_e32 vcc, -1, v165
	v_cmp_gt_i32_e64 s[8:9], 1, v0
	s_and_b64 s[10:11], s[8:9], vcc
	v_min_u32_e32 v241, 0x7f, v165
	v_lshl_add_u32 v241, v241, 2, s3
	v_cndmask_b32_e64 v241, v242, v241, s[10:11]
	ds_read_b32 v241, v241
	s_waitcnt lgkmcnt(0)
	v_add_f32_e32 v80, v50, v210
	v_add_f32_e32 v79, v34, v211
	v_add_f32_e32 v50, v51, v212
	v_add_f32_e32 v34, v35, v213
	v_add_f32_e32 v51, v52, v214
	v_add_f32_e32 v35, v36, v215
	v_add_f32_e32 v52, v53, v216
	v_add_f32_e32 v36, v37, v217
	v_add_f32_e32 v53, v54, v218
	v_add_f32_e32 v37, v38, v219
	v_add_f32_e32 v54, v55, v220
	v_add_f32_e32 v38, v39, v221
	v_add_f32_e32 v55, v56, v222
	v_add_f32_e32 v39, v40, v223
	v_add_f32_e32 v56, v57, v224
	v_add_f32_e32 v40, v41, v225
	v_add_f32_e32 v57, v58, v226
	v_add_f32_e32 v41, v42, v227
	v_add_f32_e32 v58, v59, v228
	v_add_f32_e32 v42, v43, v229
	v_add_f32_e32 v59, v60, v230
	v_add_f32_e32 v43, v44, v231
	v_add_f32_e32 v60, v61, v232
	v_add_f32_e32 v44, v45, v233
	v_add_f32_e32 v61, v62, v234
	v_add_f32_e32 v45, v46, v235
	v_add_f32_e32 v62, v63, v236
	v_add_f32_e32 v46, v47, v237
	v_add_f32_e32 v63, v64, v238
	v_add_f32_e32 v47, v48, v239
	v_add_f32_e32 v64, v65, v240
	v_add_f32_e32 v48, v49, v241
	v_max3_f32 v0, v191, v80, v79
	v_max_f32_e32 v65, v75, v75
	v_max3_f32 v0, v0, v50, v34
	v_max3_f32 v0, v0, v51, v35
	v_max3_f32 v0, v0, v52, v36
	v_max3_f32 v0, v0, v53, v37
	v_max3_f32 v0, v0, v54, v38
	v_max3_f32 v0, v0, v55, v39
	v_max3_f32 v0, v0, v56, v40
	v_max3_f32 v0, v0, v57, v41
	v_max3_f32 v0, v0, v58, v42
	v_max3_f32 v0, v0, v59, v43
	v_max3_f32 v0, v0, v60, v44
	v_max3_f32 v0, v0, v61, v45
	v_max3_f32 v0, v0, v62, v46
	v_max3_f32 v0, v0, v63, v47
	v_max3_f32 v0, v0, v64, v48
	ds_bpermute_b32 v49, v197, v0
	v_max_f32_e32 v0, v0, v0
	s_waitcnt lgkmcnt(0)
	v_max_f32_e32 v49, v49, v49
	v_max_f32_e32 v49, v0, v49
	v_max_f32_e32 v118, v65, v49
	v_sub_f32_e32 v35, v35, v118
	v_exp_f32_e32 v92, v35
	v_sub_f32_e32 v35, v52, v118
	v_exp_f32_e32 v125, v35
	v_sub_f32_e32 v35, v36, v118
	v_sub_f32_e32 v36, v53, v118
	v_exp_f32_e32 v136, v36
	v_sub_f32_e32 v36, v37, v118
	v_exp_f32_e32 v94, v36
	v_sub_f32_e32 v36, v54, v118
	v_exp_f32_e32 v138, v36
	v_sub_f32_e32 v36, v38, v118
	v_exp_f32_e32 v95, v36
	v_sub_f32_e32 v36, v55, v118
	v_exp_f32_e32 v141, v36
	v_sub_f32_e32 v36, v39, v118
	v_exp_f32_e32 v96, v36
	v_sub_f32_e32 v36, v56, v118
	v_sub_f32_e32 v0, v80, v118
	v_exp_f32_e32 v142, v36
	v_sub_f32_e32 v36, v40, v118
	v_sub_f32_e32 v65, v79, v118
	v_exp_f32_e32 v116, v0
	v_sub_f32_e32 v0, v50, v118
	v_exp_f32_e32 v97, v36
	v_sub_f32_e32 v36, v57, v118
	v_exp_f32_e32 v90, v65
	v_exp_f32_e32 v119, v0
	v_sub_f32_e32 v0, v34, v118
	v_exp_f32_e32 v120, v36
	v_sub_f32_e32 v36, v41, v118
	v_exp_f32_e32 v91, v0
	v_sub_f32_e32 v51, v51, v118
	v_exp_f32_e32 v114, v36
	v_sub_f32_e32 v36, v58, v118
	v_exp_f32_e32 v123, v51
	v_exp_f32_e32 v122, v36
	v_sub_f32_e32 v36, v42, v118
	v_exp_f32_e32 v93, v35
	v_exp_f32_e32 v115, v36
	v_sub_f32_e32 v36, v59, v118
	v_add_f32_e32 v34, v116, v90
	v_exp_f32_e32 v126, v36
	v_sub_f32_e32 v36, v43, v118
	v_add_f32_e32 v34, 0, v34
	v_add_f32_e32 v50, v119, v91
	v_exp_f32_e32 v117, v36
	v_sub_f32_e32 v36, v60, v118
	v_add_f32_e32 v34, v50, v34
	v_add_f32_e32 v35, v123, v92
	v_exp_f32_e32 v128, v36
	v_sub_f32_e32 v36, v44, v118
	v_add_f32_e32 v34, v35, v34
	v_add_f32_e32 v35, v125, v93
	v_exp_f32_e32 v121, v36
	v_sub_f32_e32 v36, v61, v118
	v_add_f32_e32 v34, v35, v34
	v_add_f32_e32 v35, v136, v94
	v_exp_f32_e32 v139, v36
	v_sub_f32_e32 v36, v45, v118
	v_add_f32_e32 v34, v35, v34
	v_add_f32_e32 v35, v138, v95
	v_exp_f32_e32 v124, v36
	v_sub_f32_e32 v36, v62, v118
	v_add_f32_e32 v34, v35, v34
	v_add_f32_e32 v35, v141, v96
	v_exp_f32_e32 v140, v36
	v_sub_f32_e32 v36, v46, v118
	v_add_f32_e32 v34, v35, v34
	v_add_f32_e32 v35, v142, v97
	v_exp_f32_e32 v127, v36
	v_sub_f32_e32 v36, v63, v118
	v_add_f32_e32 v34, v35, v34
	v_add_f32_e32 v35, v120, v114
	v_exp_f32_e32 v143, v36
	v_sub_f32_e32 v36, v47, v118
	v_add_f32_e32 v34, v35, v34
	v_add_f32_e32 v35, v122, v115
	v_exp_f32_e32 v129, v36
	v_sub_f32_e32 v36, v64, v118
	v_add_f32_e32 v34, v35, v34
	v_add_f32_e32 v35, v126, v117
	v_exp_f32_e32 v144, v36
	v_sub_f32_e32 v36, v48, v118
	v_add_f32_e32 v34, v35, v34
	v_add_f32_e32 v35, v128, v121
	v_exp_f32_e32 v137, v36
	v_add_f32_e32 v34, v35, v34
	v_add_f32_e32 v35, v139, v124
	v_add_f32_e32 v34, v35, v34
	v_add_f32_e32 v35, v140, v127
	v_add_f32_e32 v34, v35, v34
	v_add_f32_e32 v35, v143, v129
	v_add_f32_e32 v34, v35, v34
	v_add_f32_e32 v35, v144, v137
	v_add_f32_e32 v34, v35, v34
	v_sub_f32_e32 v0, v75, v118
	ds_bpermute_b32 v35, v197, v34
	v_exp_f32_e32 v0, v0
	v_cmp_gt_f32_e32 vcc, v49, v75
	s_cbranch_vccz .LBB0_1382
	v_pk_mul_f32 v[32:33], v[32:33], v[0:1] op_sel_hi:[1,0]
	v_pk_mul_f32 v[30:31], v[30:31], v[0:1] op_sel_hi:[1,0]
	v_pk_mul_f32 v[28:29], v[28:29], v[0:1] op_sel_hi:[1,0]
	v_pk_mul_f32 v[26:27], v[26:27], v[0:1] op_sel_hi:[1,0]
	v_pk_mul_f32 v[24:25], v[24:25], v[0:1] op_sel_hi:[1,0]
	v_pk_mul_f32 v[22:23], v[22:23], v[0:1] op_sel_hi:[1,0]
	v_pk_mul_f32 v[20:21], v[20:21], v[0:1] op_sel_hi:[1,0]
	v_pk_mul_f32 v[18:19], v[18:19], v[0:1] op_sel_hi:[1,0]
	v_pk_mul_f32 v[16:17], v[16:17], v[0:1] op_sel_hi:[1,0]
	v_pk_mul_f32 v[14:15], v[14:15], v[0:1] op_sel_hi:[1,0]
	v_pk_mul_f32 v[12:13], v[12:13], v[0:1] op_sel_hi:[1,0]
	v_pk_mul_f32 v[10:11], v[10:11], v[0:1] op_sel_hi:[1,0]
	v_pk_mul_f32 v[8:9], v[8:9], v[0:1] op_sel_hi:[1,0]
	v_pk_mul_f32 v[6:7], v[6:7], v[0:1] op_sel_hi:[1,0]
	v_pk_mul_f32 v[4:5], v[4:5], v[0:1] op_sel_hi:[1,0]
	v_pk_mul_f32 v[2:3], v[2:3], v[0:1] op_sel_hi:[1,0]

.Lp2_loop:
	s_lshr_b32 s8, s12, 1
	s_and_b32 s13, s10, 32
	s_mul_i32 s9, s8, 0x5400
	v_or_b32_e32 v226, s13, v85
	v_mul_u32_u24_e32 v226, 0x90, v226
	v_add3_u32 v226, s9, v226, v195
	ds_read_b128 v[150:153], v226
	ds_read_b128 v[154:157], v226 offset:32
	ds_read_b128 v[158:161], v226 offset:64
	ds_read_b128 v[162:165], v226 offset:96
	s_lshl_b32 s8, s8, 6
	s_or_b32 s8, s8, s13
	v_add_u32_e32 v145, s8, v130
	v_lshlrev_b32_e32 v227, 4, v145
	v_sub_u32_e32 v227, v88, v227
	v_add_u32_e32 v228, s11, v89
	v_add_u32_e32 v228, 0x1c000, v228
	s_waitcnt lgkmcnt(3)
	v_mfma_f32_32x32x16_bf16 v[34:49], v[150:153], v[98:101], 0
	s_waitcnt lgkmcnt(2)
	v_mfma_f32_32x32x16_bf16 v[34:49], v[154:157], v[102:105], v[34:49]
	s_waitcnt lgkmcnt(1)
	v_mfma_f32_32x32x16_bf16 v[34:49], v[158:161], v[106:109], v[34:49]
	s_waitcnt lgkmcnt(0)
	v_mfma_f32_32x32x16_bf16 v[34:49], v[162:165], v[110:113], v[34:49]
	v_cmp_gt_i32_e32 vcc, s82, v145
	v_cmp_lt_i32_e64 s[8:9], -1, v227
	s_and_b64 vcc, vcc, s[8:9]
	v_min_u32_e32 v210, 0x7f, v227
	v_lshl_add_u32 v210, v210, 2, s3
	v_cndmask_b32_e32 v210, v242, v210, vcc
	ds_read_b32 v210, v210
	v_add_u32_e32 v229, 1, v145
	v_cmp_gt_i32_e32 vcc, s82, v229
	v_subrev_u32_e32 v211, 0x10, v227
	v_cmp_lt_i32_e64 s[8:9], -1, v211
	s_and_b64 vcc, vcc, s[8:9]
	v_min_u32_e32 v211, 0x7f, v211
	v_lshl_add_u32 v211, v211, 2, s3
	v_cndmask_b32_e32 v211, v242, v211, vcc
	ds_read_b32 v211, v211
	v_add_u32_e32 v229, 2, v145
	v_cmp_gt_i32_e32 vcc, s82, v229
	v_subrev_u32_e32 v212, 0x20, v227
	v_cmp_lt_i32_e64 s[8:9], -1, v212
	s_and_b64 vcc, vcc, s[8:9]
	v_min_u32_e32 v212, 0x7f, v212
	v_lshl_add_u32 v212, v212, 2, s3
	v_cndmask_b32_e32 v212, v242, v212, vcc
	ds_read_b32 v212, v212
	v_add_u32_e32 v229, 3, v145
	v_cmp_gt_i32_e32 vcc, s82, v229
	v_subrev_u32_e32 v213, 0x30, v227
	v_cmp_lt_i32_e64 s[8:9], -1, v213
	s_and_b64 vcc, vcc, s[8:9]
	v_min_u32_e32 v213, 0x7f, v213
	v_lshl_add_u32 v213, v213, 2, s3
	v_cndmask_b32_e32 v213, v242, v213, vcc
	ds_read_b32 v213, v213
	v_add_u32_e32 v229, 8, v145
	v_cmp_gt_i32_e32 vcc, s82, v229
	v_subrev_u32_e32 v214, 0x80, v227
	v_cmp_lt_i32_e64 s[8:9], -1, v214
	s_and_b64 vcc, vcc, s[8:9]
	v_min_u32_e32 v214, 0x7f, v214
	v_lshl_add_u32 v214, v214, 2, s3
	v_cndmask_b32_e32 v214, v242, v214, vcc
	ds_read_b32 v214, v214
	v_add_u32_e32 v229, 9, v145
	v_cmp_gt_i32_e32 vcc, s82, v229
	v_subrev_u32_e32 v215, 0x90, v227
	v_cmp_lt_i32_e64 s[8:9], -1, v215
	s_and_b64 vcc, vcc, s[8:9]
	v_min_u32_e32 v215, 0x7f, v215
	v_lshl_add_u32 v215, v215, 2, s3
	v_cndmask_b32_e32 v215, v242, v215, vcc
	ds_read_b32 v215, v215
	v_add_u32_e32 v229, 10, v145
	v_cmp_gt_i32_e32 vcc, s82, v229
	v_subrev_u32_e32 v216, 0xa0, v227
	v_cmp_lt_i32_e64 s[8:9], -1, v216
	s_and_b64 vcc, vcc, s[8:9]
	v_min_u32_e32 v216, 0x7f, v216
	v_lshl_add_u32 v216, v216, 2, s3
	v_cndmask_b32_e32 v216, v242, v216, vcc
	ds_read_b32 v216, v216
	v_add_u32_e32 v229, 11, v145
	v_cmp_gt_i32_e32 vcc, s82, v229
	v_subrev_u32_e32 v217, 0xb0, v227
	v_cmp_lt_i32_e64 s[8:9], -1, v217
	s_and_b64 vcc, vcc, s[8:9]
	v_min_u32_e32 v217, 0x7f, v217
	v_lshl_add_u32 v217, v217, 2, s3
	v_cndmask_b32_e32 v217, v242, v217, vcc
	ds_read_b32 v217, v217
	v_add_u32_e32 v229, 16, v145
	v_cmp_gt_i32_e32 vcc, s82, v229
	v_subrev_u32_e32 v218, 0x100, v227
	v_cmp_lt_i32_e64 s[8:9], -1, v218
	s_and_b64 vcc, vcc, s[8:9]
	v_min_u32_e32 v218, 0x7f, v218
	v_lshl_add_u32 v218, v218, 2, s3
	v_cndmask_b32_e32 v218, v242, v218, vcc
	ds_read_b32 v218, v218
	v_add_u32_e32 v229, 17, v145
	v_cmp_gt_i32_e32 vcc, s82, v229
	v_subrev_u32_e32 v219, 0x110, v227
	v_cmp_lt_i32_e64 s[8:9], -1, v219
	s_and_b64 vcc, vcc, s[8:9]
	v_min_u32_e32 v219, 0x7f, v219
	v_lshl_add_u32 v219, v219, 2, s3
	v_cndmask_b32_e32 v219, v242, v219, vcc
	ds_read_b32 v219, v219
	v_add_u32_e32 v229, 18, v145
	v_cmp_gt_i32_e32 vcc, s82, v229
	v_subrev_u32_e32 v220, 0x120, v227
	v_cmp_lt_i32_e64 s[8:9], -1, v220
	s_and_b64 vcc, vcc, s[8:9]
	v_min_u32_e32 v220, 0x7f, v220
	v_lshl_add_u32 v220, v220, 2, s3
	v_cndmask_b32_e32 v220, v242, v220, vcc
	ds_read_b32 v220, v220
	v_add_u32_e32 v229, 19, v145
	v_cmp_gt_i32_e32 vcc, s82, v229
	v_subrev_u32_e32 v221, 0x130, v227
	v_cmp_lt_i32_e64 s[8:9], -1, v221
	s_and_b64 vcc, vcc, s[8:9]
	v_min_u32_e32 v221, 0x7f, v221
	v_lshl_add_u32 v221, v221, 2, s3
	v_cndmask_b32_e32 v221, v242, v221, vcc
	ds_read_b32 v221, v221
	v_add_u32_e32 v229, 24, v145
	v_cmp_gt_i32_e32 vcc, s82, v229
	v_subrev_u32_e32 v222, 0x180, v227
	v_cmp_lt_i32_e64 s[8:9], -1, v222
	s_and_b64 vcc, vcc, s[8:9]
	v_min_u32_e32 v222, 0x7f, v222
	v_lshl_add_u32 v222, v222, 2, s3
	v_cndmask_b32_e32 v222, v242, v222, vcc
	ds_read_b32 v222, v222
	v_add_u32_e32 v229, 25, v145
	v_cmp_gt_i32_e32 vcc, s82, v229
	v_subrev_u32_e32 v223, 0x190, v227
	v_cmp_lt_i32_e64 s[8:9], -1, v223
	s_and_b64 vcc, vcc, s[8:9]
	v_min_u32_e32 v223, 0x7f, v223
	v_lshl_add_u32 v223, v223, 2, s3
	v_cndmask_b32_e32 v223, v242, v223, vcc
	ds_read_b32 v223, v223
	v_add_u32_e32 v229, 26, v145
	v_cmp_gt_i32_e32 vcc, s82, v229
	v_subrev_u32_e32 v224, 0x1a0, v227
	v_cmp_lt_i32_e64 s[8:9], -1, v224
	s_and_b64 vcc, vcc, s[8:9]
	v_min_u32_e32 v224, 0x7f, v224
	v_lshl_add_u32 v224, v224, 2, s3
	v_cndmask_b32_e32 v224, v242, v224, vcc
	ds_read_b32 v224, v224
	v_add_u32_e32 v229, 27, v145
	v_cmp_gt_i32_e32 vcc, s82, v229
	v_subrev_u32_e32 v225, 0x1b0, v227
	v_cmp_lt_i32_e64 s[8:9], -1, v225
	s_and_b64 vcc, vcc, s[8:9]
	v_min_u32_e32 v225, 0x7f, v225
	v_lshl_add_u32 v225, v225, 2, s3
	v_cndmask_b32_e32 v225, v242, v225, vcc
	ds_read_b32 v225, v225
	s_waitcnt lgkmcnt(0)
	v_add_f32_e32 v210, v34, v210
	v_sub_f32_e32 v210, v210, v118
	v_exp_f32_e32 v210, v210
	v_add_f32_e32 v211, v35, v211
	v_sub_f32_e32 v211, v211, v118
	v_exp_f32_e32 v211, v211
	v_add_f32_e32 v212, v36, v212
	v_sub_f32_e32 v212, v212, v118
	v_exp_f32_e32 v212, v212
	v_add_f32_e32 v213, v37, v213
	v_sub_f32_e32 v213, v213, v118
	v_exp_f32_e32 v213, v213
	v_add_f32_e32 v214, v38, v214
	v_sub_f32_e32 v214, v214, v118
	v_exp_f32_e32 v214, v214
	v_add_f32_e32 v215, v39, v215
	v_sub_f32_e32 v215, v215, v118
	v_exp_f32_e32 v215, v215
	v_add_f32_e32 v216, v40, v216
	v_sub_f32_e32 v216, v216, v118
	v_exp_f32_e32 v216, v216
	v_add_f32_e32 v217, v41, v217
	v_sub_f32_e32 v217, v217, v118
	v_exp_f32_e32 v217, v217
	v_add_f32_e32 v218, v42, v218
	v_sub_f32_e32 v218, v218, v118
	v_exp_f32_e32 v218, v218
	v_add_f32_e32 v219, v43, v219
	v_sub_f32_e32 v219, v219, v118
	v_exp_f32_e32 v219, v219
	v_add_f32_e32 v220, v44, v220
	v_sub_f32_e32 v220, v220, v118
	v_exp_f32_e32 v220, v220
	v_add_f32_e32 v221, v45, v221
	v_sub_f32_e32 v221, v221, v118
	v_exp_f32_e32 v221, v221
	v_add_f32_e32 v222, v46, v222
	v_sub_f32_e32 v222, v222, v118
	v_exp_f32_e32 v222, v222
	v_add_f32_e32 v223, v47, v223
	v_sub_f32_e32 v223, v223, v118
	v_exp_f32_e32 v223, v223
	v_add_f32_e32 v224, v48, v224
	v_sub_f32_e32 v224, v224, v118
	v_exp_f32_e32 v224, v224
	v_add_f32_e32 v225, v49, v225
	v_sub_f32_e32 v225, v225, v118
	v_exp_f32_e32 v225, v225
	v_mul_f32_e32 v210, v0, v210
	v_fma_f32 v210, v210, s87, 0.5
	v_cvt_u32_f32_e32 v210, v210
	ds_add_u32 v228, v210
	v_mul_f32_e32 v211, v0, v211
	v_fma_f32 v211, v211, s87, 0.5
	v_cvt_u32_f32_e32 v211, v211
	ds_add_u32 v228, v211 offset:4
	v_mul_f32_e32 v212, v0, v212
	v_fma_f32 v212, v212, s87, 0.5
	v_cvt_u32_f32_e32 v212, v212
	ds_add_u32 v228, v212 offset:8
	v_mul_f32_e32 v213, v0, v213
	v_fma_f32 v213, v213, s87, 0.5
	v_cvt_u32_f32_e32 v213, v213
	ds_add_u32 v228, v213 offset:12
	v_mul_f32_e32 v214, v0, v214
	v_fma_f32 v214, v214, s87, 0.5
	v_cvt_u32_f32_e32 v214, v214
	ds_add_u32 v228, v214 offset:32
	v_mul_f32_e32 v215, v0, v215
	v_fma_f32 v215, v215, s87, 0.5
	v_cvt_u32_f32_e32 v215, v215
	ds_add_u32 v228, v215 offset:36
	v_mul_f32_e32 v216, v0, v216
	v_fma_f32 v216, v216, s87, 0.5
	v_cvt_u32_f32_e32 v216, v216
	ds_add_u32 v228, v216 offset:40
	v_mul_f32_e32 v217, v0, v217
	v_fma_f32 v217, v217, s87, 0.5
	v_cvt_u32_f32_e32 v217, v217
	ds_add_u32 v228, v217 offset:44
	v_mul_f32_e32 v218, v0, v218
	v_fma_f32 v218, v218, s87, 0.5
	v_cvt_u32_f32_e32 v218, v218
	ds_add_u32 v228, v218 offset:64
	v_mul_f32_e32 v219, v0, v219
	v_fma_f32 v219, v219, s87, 0.5
	v_cvt_u32_f32_e32 v219, v219
	ds_add_u32 v228, v219 offset:68
	v_mul_f32_e32 v220, v0, v220
	v_fma_f32 v220, v220, s87, 0.5
	v_cvt_u32_f32_e32 v220, v220
	ds_add_u32 v228, v220 offset:72
	v_mul_f32_e32 v221, v0, v221
	v_fma_f32 v221, v221, s87, 0.5
	v_cvt_u32_f32_e32 v221, v221
	ds_add_u32 v228, v221 offset:76
	v_mul_f32_e32 v222, v0, v222
	v_fma_f32 v222, v222, s87, 0.5
	v_cvt_u32_f32_e32 v222, v222
	ds_add_u32 v228, v222 offset:96
	v_mul_f32_e32 v223, v0, v223
	v_fma_f32 v223, v223, s87, 0.5
	v_cvt_u32_f32_e32 v223, v223
	ds_add_u32 v228, v223 offset:100
	v_mul_f32_e32 v224, v0, v224
	v_fma_f32 v224, v224, s87, 0.5
	v_cvt_u32_f32_e32 v224, v224
	ds_add_u32 v228, v224 offset:104
	v_mul_f32_e32 v225, v0, v225
	v_fma_f32 v225, v225, s87, 0.5
	v_cvt_u32_f32_e32 v225, v225
	ds_add_u32 v228, v225 offset:108
	s_add_i32 s12, s12, 1
	s_addk_i32 s11, 0x80
	s_add_i32 s10, s10, 32
	s_cmpk_lg_i32 s11, 0x200
	s_cbranch_scc1 .Lp2_loop
